# SwiGLU GEMM K-loop: LDS-DMA loads use SGPR base + 32-bit VGPR offset (16 fewer 64-bit VALU adds per iteration)
# speedup vs baseline: 1.0343x; 1.0007x over previous
; #define PG8_STAGE(bufoff, gbase, voff) do { _Pragma("unroll") for (int _i = 0; _i < 2; ++_i) \
;         __builtin_amdgcn_global_load_lds((const unsigned*)((const char*)(gbase) + (voff)[_i]), (PG8_LAS unsigned*)(lds + (bufoff) + ldsw + _i * 8192), 16, 0, 0); } while (0)
; #define PG8_LDA(dst, b, h) do { _Pragma("unroll") for (int m = 0; m < 4; ++m) _Pragma("unroll") for (int k = 0; k < 2; ++k) dst[m][k] = *(const PG8_LAS bf16x8*)(lds + PG8_SA(b, h) + aoff + m * 2048 + k * 1024); } while (0)
; #define PG8_LDB(dst, b, h) do { _Pragma("unroll") for (int n = 0; n < 2; ++n) _Pragma("unroll") for (int k = 0; k < 2; ++k) dst[n][k] = *(const PG8_LAS bf16x8*)(lds + PG8_SB(b, h) + boff + n * 2048 + k * 1024); } while (0)
; #define PG8_MMA(ai, bj, At, Bt) do { __builtin_amdgcn_s_setprio(1); _Pragma("unroll") for (int m = 0; m < 4; ++m) _Pragma("unroll") for (int n = 0; n < 2; ++n) _Pragma("unroll") for (int k = 0; k < 2; ++k) \
;         acc[ai][bj][m][n] = __builtin_amdgcn_mfma_f32_16x16x32_bf16(Bt[n][k], At[m][k], acc[ai][bj][m][n], 0, 0, 0); __builtin_amdgcn_s_setprio(0); } while (0)
; #define PG8_WAIT_V(n) asm volatile("s_waitcnt vmcnt(" #n ")" ::: "memory")
; #define PG8_WAIT_L(n) asm volatile("s_waitcnt lgkmcnt(" #n ")" ::: "memory")
; #define PG8_BAR __builtin_amdgcn_s_barrier()
; #define PG8_SCHED __builtin_amdgcn_sched_barrier(0)
; template <class Epi, class Sched, bool ALIGN_EPI = false, bool SP2 = false>
; __device__ __forceinline__ void gemm_phase(PG8_LAS unsigned char* lds, const Gemm g, const Sched& S, const Epi& E, const int tid) {
;     ...
;             PG8_LDB(B0, 0, 0); PG8_LDB(B1, 0, 1); PG8_SCHED; PG8_LDA(At, 0, 0); PG8_STAGE(PG8_SA(1, 1), a1 + hstep, voffA);
;             PG8_WAIT_V(8); PG8_WAIT_L(0); PG8_BAR; PG8_MMA(0, 0, At, B0); PG8_MMA(0, 1, At, B1); PG8_BAR; PG8_SCHED;
;             PG8_LDA(At, 0, 1); PG8_STAGE(PG8_SB(0, 0), b2, voffB); PG8_STAGE(PG8_SB(0, 1), b2 + hstep, voffB); PG8_STAGE(PG8_SA(0, 0), a2, voffA);
;             PG8_WAIT_V(8); PG8_WAIT_L(0); PG8_BAR; PG8_MMA(1, 0, At, B0); PG8_MMA(1, 1, At, B1); PG8_BAR; PG8_SCHED;
.LBB0_1492:
	s_add_u32 s20, s18, 0xfffc0080
	s_addc_u32 s21, s19, -1
	s_add_i32 s60, 0, 0x10000
	s_cmp_eq_u32 s59, 12
	s_cselect_b32 s53, s11, s21
	s_cselect_b32 s52, s55, s20
	s_cselect_b32 s21, s9, s58
	s_cselect_b32 s20, s56, s57
	s_add_i32 s62, 0, 0x14000
	v_add_u32_e32 v154, s60, v143
	v_add_u32_e32 v162, s62, v143
	ds_read_b128 v[138:141], v154
	ds_read_b128 v[146:149], v154 offset:1024
	ds_read_b128 v[150:153], v154 offset:2048
	ds_read_b128 v[154:157], v154 offset:3072
	ds_read_b128 v[158:161], v162
	ds_read_b128 v[180:183], v162 offset:1024
	ds_read_b128 v[184:187], v162 offset:2048
	ds_read_b128 v[188:191], v162 offset:3072
	s_add_i32 m0, s43, 0xc000
	ds_read_b128 v[192:195], v145
	ds_read_b128 v[196:199], v145 offset:1024
	ds_read_b128 v[214:217], v145 offset:2048
	ds_read_b128 v[218:221], v145 offset:3072
	ds_read_b128 v[222:225], v145 offset:4096
	ds_read_b128 v[226:229], v145 offset:5120
	ds_read_b128 v[230:233], v145 offset:6144
	ds_read_b128 v[234:237], v145 offset:7168
	global_load_lds_dwordx4 v136, s[18:19]
	s_add_i32 m0, s43, 0xe000
	s_nop 0
	global_load_lds_dwordx4 v134, s[18:19]
	s_waitcnt vmcnt(8)
	s_waitcnt lgkmcnt(0)
	s_barrier
	s_setprio 1
	s_waitcnt lgkmcnt(0)
	v_mfma_f32_16x16x32_bf16 v[124:127], v[138:141], v[192:195], v[124:127]
	v_mfma_f32_16x16x32_bf16 v[116:119], v[150:153], v[192:195], v[116:119]
	v_mfma_f32_16x16x32_bf16 v[108:111], v[138:141], v[214:217], v[108:111]
	v_mfma_f32_16x16x32_bf16 v[100:103], v[150:153], v[214:217], v[100:103]
	v_mfma_f32_16x16x32_bf16 v[92:95], v[138:141], v[222:225], v[92:95]
	v_mfma_f32_16x16x32_bf16 v[84:87], v[150:153], v[222:225], v[84:87]
	v_mfma_f32_16x16x32_bf16 v[76:79], v[138:141], v[230:233], v[76:79]
	v_mfma_f32_16x16x32_bf16 v[68:71], v[150:153], v[230:233], v[68:71]
	v_mfma_f32_16x16x32_bf16 v[124:127], v[146:149], v[196:199], v[124:127]
	v_mfma_f32_16x16x32_bf16 v[116:119], v[154:157], v[196:199], v[116:119]
	v_mfma_f32_16x16x32_bf16 v[108:111], v[146:149], v[218:221], v[108:111]
	v_mfma_f32_16x16x32_bf16 v[100:103], v[154:157], v[218:221], v[100:103]
	v_mfma_f32_16x16x32_bf16 v[92:95], v[146:149], v[226:229], v[92:95]
	v_mfma_f32_16x16x32_bf16 v[84:87], v[154:157], v[226:229], v[84:87]
	v_mfma_f32_16x16x32_bf16 v[76:79], v[146:149], v[234:237], v[76:79]
	v_mfma_f32_16x16x32_bf16 v[68:71], v[154:157], v[234:237], v[68:71]
	s_setprio 0
	s_setprio 1
	v_mfma_f32_16x16x32_bf16 v[120:123], v[158:161], v[192:195], v[120:123]
	v_mfma_f32_16x16x32_bf16 v[112:115], v[184:187], v[192:195], v[112:115]
	v_mfma_f32_16x16x32_bf16 v[104:107], v[158:161], v[214:217], v[104:107]
	v_mfma_f32_16x16x32_bf16 v[96:99], v[184:187], v[214:217], v[96:99]
	v_mfma_f32_16x16x32_bf16 v[88:91], v[158:161], v[222:225], v[88:91]
	v_mfma_f32_16x16x32_bf16 v[80:83], v[184:187], v[222:225], v[80:83]
	v_mfma_f32_16x16x32_bf16 v[72:75], v[158:161], v[230:233], v[72:75]
	v_mfma_f32_16x16x32_bf16 v[64:67], v[184:187], v[230:233], v[64:67]
	v_mfma_f32_16x16x32_bf16 v[120:123], v[180:183], v[196:199], v[120:123]
	v_mfma_f32_16x16x32_bf16 v[112:115], v[188:191], v[196:199], v[112:115]
	v_mfma_f32_16x16x32_bf16 v[104:107], v[180:183], v[218:221], v[104:107]
	v_mfma_f32_16x16x32_bf16 v[96:99], v[188:191], v[218:221], v[96:99]
	v_mfma_f32_16x16x32_bf16 v[88:91], v[180:183], v[226:229], v[88:91]
	v_mfma_f32_16x16x32_bf16 v[80:83], v[188:191], v[226:229], v[80:83]
	v_mfma_f32_16x16x32_bf16 v[72:75], v[180:183], v[234:237], v[72:75]
	v_mfma_f32_16x16x32_bf16 v[64:67], v[188:191], v[234:237], v[64:67]
	s_setprio 0
	s_barrier
	s_add_i32 s60, s60, s41
	s_mov_b32 m0, s60
	ds_read_b128 v[192:195], v145 offset:16384
	ds_read_b128 v[196:199], v145 offset:17408
	ds_read_b128 v[214:217], v145 offset:18432
	ds_read_b128 v[218:221], v145 offset:19456
	ds_read_b128 v[222:225], v145 offset:20480
	ds_read_b128 v[226:229], v145 offset:21504
	ds_read_b128 v[230:233], v145 offset:22528
	ds_read_b128 v[234:237], v145 offset:23552
	global_load_lds_dwordx4 v164, s[20:21]
	s_add_i32 m0, s60, 0x2000
	s_add_u32 s60, s20, 0x40000
	s_addc_u32 s61, s21, 0
	s_add_i32 s62, s62, s41
	global_load_lds_dwordx4 v128, s[20:21]
	s_mov_b32 m0, s62
	s_nop 0
	global_load_lds_dwordx4 v164, s[60:61]
	s_add_i32 m0, s62, 0x2000
	s_nop 0
	global_load_lds_dwordx4 v128, s[60:61]
	s_mov_b32 m0, s43
	s_nop 0
	global_load_lds_dwordx4 v132, s[52:53]
	s_mov_b32 m0, s44
	s_nop 0
	global_load_lds_dwordx4 v130, s[52:53]
	s_waitcnt vmcnt(8)
	s_waitcnt lgkmcnt(0)
	s_barrier
	s_setprio 1
	s_waitcnt lgkmcnt(0)
	v_mfma_f32_16x16x32_bf16 v[60:63], v[138:141], v[192:195], v[60:63]
	v_mfma_f32_16x16x32_bf16 v[52:55], v[150:153], v[192:195], v[52:55]
	v_mfma_f32_16x16x32_bf16 v[44:47], v[138:141], v[214:217], v[44:47]
	v_mfma_f32_16x16x32_bf16 v[36:39], v[150:153], v[214:217], v[36:39]
	v_mfma_f32_16x16x32_bf16 v[28:31], v[138:141], v[222:225], v[28:31]
	v_mfma_f32_16x16x32_bf16 v[20:23], v[150:153], v[222:225], v[20:23]
	v_mfma_f32_16x16x32_bf16 v[12:15], v[138:141], v[230:233], v[12:15]
	v_mfma_f32_16x16x32_bf16 v[4:7], v[150:153], v[230:233], v[4:7]
	v_mfma_f32_16x16x32_bf16 v[60:63], v[146:149], v[196:199], v[60:63]
	v_mfma_f32_16x16x32_bf16 v[52:55], v[154:157], v[196:199], v[52:55]
	v_mfma_f32_16x16x32_bf16 v[44:47], v[146:149], v[218:221], v[44:47]
	v_mfma_f32_16x16x32_bf16 v[36:39], v[154:157], v[218:221], v[36:39]
	v_mfma_f32_16x16x32_bf16 v[28:31], v[146:149], v[226:229], v[28:31]
	v_mfma_f32_16x16x32_bf16 v[20:23], v[154:157], v[226:229], v[20:23]
	v_mfma_f32_16x16x32_bf16 v[12:15], v[146:149], v[234:237], v[12:15]
	v_mfma_f32_16x16x32_bf16 v[4:7], v[154:157], v[234:237], v[4:7]
	s_setprio 0
	s_setprio 1
	v_mfma_f32_16x16x32_bf16 v[56:59], v[158:161], v[192:195], v[56:59]
	v_mfma_f32_16x16x32_bf16 v[48:51], v[184:187], v[192:195], v[48:51]
	v_mfma_f32_16x16x32_bf16 v[40:43], v[158:161], v[214:217], v[40:43]
	v_mfma_f32_16x16x32_bf16 v[32:35], v[184:187], v[214:217], v[32:35]
	v_mfma_f32_16x16x32_bf16 v[24:27], v[158:161], v[222:225], v[24:27]
	v_mfma_f32_16x16x32_bf16 v[16:19], v[184:187], v[222:225], v[16:19]
	v_mfma_f32_16x16x32_bf16 v[8:11], v[158:161], v[230:233], v[8:11]
	v_mfma_f32_16x16x32_bf16 v[0:3], v[184:187], v[230:233], v[0:3]
	v_mfma_f32_16x16x32_bf16 v[56:59], v[180:183], v[196:199], v[56:59]
	v_mfma_f32_16x16x32_bf16 v[48:51], v[188:191], v[196:199], v[48:51]
	v_mfma_f32_16x16x32_bf16 v[40:43], v[180:183], v[218:221], v[40:43]
	v_mfma_f32_16x16x32_bf16 v[32:35], v[188:191], v[218:221], v[32:35]
	v_mfma_f32_16x16x32_bf16 v[24:27], v[180:183], v[226:229], v[24:27]
	v_mfma_f32_16x16x32_bf16 v[16:19], v[188:191], v[226:229], v[16:19]
	v_mfma_f32_16x16x32_bf16 v[8:11], v[180:183], v[234:237], v[8:11]
	v_mfma_f32_16x16x32_bf16 v[0:3], v[188:191], v[234:237], v[0:3]
	s_setprio 0
	s_barrier
; #define PG8_STAGE(bufoff, gbase, voff) do { _Pragma("unroll") for (int _i = 0; _i < 2; ++_i) \
;         __builtin_amdgcn_global_load_lds((const unsigned*)((const char*)(gbase) + (voff)[_i]), (PG8_LAS unsigned*)(lds + (bufoff) + ldsw + _i * 8192), 16, 0, 0); } while (0)
; #define PG8_LDA(dst, b, h) do { _Pragma("unroll") for (int m = 0; m < 4; ++m) _Pragma("unroll") for (int k = 0; k < 2; ++k) dst[m][k] = *(const PG8_LAS bf16x8*)(lds + PG8_SA(b, h) + aoff + m * 2048 + k * 1024); } while (0)
; #define PG8_LDB(dst, b, h) do { _Pragma("unroll") for (int n = 0; n < 2; ++n) _Pragma("unroll") for (int k = 0; k < 2; ++k) dst[n][k] = *(const PG8_LAS bf16x8*)(lds + PG8_SB(b, h) + boff + n * 2048 + k * 1024); } while (0)
; #define PG8_MMA(ai, bj, At, Bt) do { __builtin_amdgcn_s_setprio(1); _Pragma("unroll") for (int m = 0; m < 4; ++m) _Pragma("unroll") for (int n = 0; n < 2; ++n) _Pragma("unroll") for (int k = 0; k < 2; ++k) \
;         acc[ai][bj][m][n] = __builtin_amdgcn_mfma_f32_16x16x32_bf16(Bt[n][k], At[m][k], acc[ai][bj][m][n], 0, 0, 0); __builtin_amdgcn_s_setprio(0); } while (0)
; #define PG8_WAIT_V(n) asm volatile("s_waitcnt vmcnt(" #n ")" ::: "memory")
; #define PG8_WAIT_L(n) asm volatile("s_waitcnt lgkmcnt(" #n ")" ::: "memory")
; template <class Epi, class Sched, bool ALIGN_EPI = false, bool SP2 = false>
; __device__ __forceinline__ void gemm_phase(PG8_LAS unsigned char* lds, const Gemm g, const Sched& S, const Epi& E, const int tid) {
;     ...
;         for (int t = 0; t < nt; t += 2) {
;             const bool last = (t == nt - 2);
;             const char* a1 = cA + (size_t)(t + 1) * kstep;
;             const char* a2 = last ? nA : cA + (size_t)(t + 2) * kstep; const char* b2 = last ? nB : cB + (size_t)(t + 2) * kstep;
;             const char* a3 = a2 + kstep; const char* b3 = b2 + kstep;
;             if (last && has_next) S.a_ready(nxt);
;     ...
;             PG8_LDB(B0, 1, 0); PG8_LDB(B1, 1, 1); PG8_SCHED; PG8_LDA(At, 1, 0); PG8_STAGE(PG8_SA(0, 1), a2 + hstep, voffA);
;             PG8_WAIT_V(8); PG8_WAIT_L(0); PG8_BAR; PG8_MMA(0, 0, At, B0); PG8_MMA(0, 1, At, B1); PG8_BAR; PG8_SCHED;
;             PG8_LDA(At, 1, 1); PG8_STAGE(PG8_SB(1, 0), b3, voffB); PG8_STAGE(PG8_SB(1, 1), b3 + hstep, voffB); PG8_STAGE(PG8_SA(1, 0), a3, voffA);
;             PG8_WAIT_V(8); PG8_WAIT_L(0); PG8_BAR; PG8_MMA(1, 0, At, B0); PG8_MMA(1, 1, At, B1); PG8_BAR; PG8_SCHED;
	s_add_i32 s60, 0, 0x18000
	s_add_i32 s61, 0, 0x1c000
	v_add_u32_e32 v154, s60, v143
	v_add_u32_e32 v166, s61, v143
	ds_read_b128 v[138:141], v154
	ds_read_b128 v[146:149], v154 offset:1024
	ds_read_b128 v[150:153], v154 offset:2048
	ds_read_b128 v[154:157], v154 offset:3072
	ds_read_b128 v[158:161], v166
	ds_read_b128 v[180:183], v166 offset:1024
	ds_read_b128 v[184:187], v166 offset:2048
	ds_read_b128 v[188:191], v166 offset:3072
	s_add_u32 s52, s52, 0x40000
	s_addc_u32 s53, s53, 0
	s_mov_b32 m0, s45
	ds_read_b128 v[192:195], v145 offset:32768
	ds_read_b128 v[196:199], v145 offset:33792
	ds_read_b128 v[214:217], v145 offset:34816
	ds_read_b128 v[218:221], v145 offset:35840
	ds_read_b128 v[222:225], v145 offset:36864
	ds_read_b128 v[226:229], v145 offset:37888
	ds_read_b128 v[230:233], v145 offset:38912
	ds_read_b128 v[234:237], v145 offset:39936
	global_load_lds_dwordx4 v132, s[52:53]
	s_mov_b32 m0, s48
	s_nop 0
	global_load_lds_dwordx4 v130, s[52:53]
	s_waitcnt vmcnt(8)
	s_waitcnt lgkmcnt(0)
	s_barrier
	s_setprio 1
	s_waitcnt lgkmcnt(0)
	v_mfma_f32_16x16x32_bf16 v[124:127], v[138:141], v[192:195], v[124:127]
	v_mfma_f32_16x16x32_bf16 v[116:119], v[150:153], v[192:195], v[116:119]
	v_mfma_f32_16x16x32_bf16 v[108:111], v[138:141], v[214:217], v[108:111]
	v_mfma_f32_16x16x32_bf16 v[100:103], v[150:153], v[214:217], v[100:103]
	v_mfma_f32_16x16x32_bf16 v[92:95], v[138:141], v[222:225], v[92:95]
	v_mfma_f32_16x16x32_bf16 v[84:87], v[150:153], v[222:225], v[84:87]
	v_mfma_f32_16x16x32_bf16 v[76:79], v[138:141], v[230:233], v[76:79]
	v_mfma_f32_16x16x32_bf16 v[68:71], v[150:153], v[230:233], v[68:71]
	v_mfma_f32_16x16x32_bf16 v[124:127], v[146:149], v[196:199], v[124:127]
	v_mfma_f32_16x16x32_bf16 v[116:119], v[154:157], v[196:199], v[116:119]
	v_mfma_f32_16x16x32_bf16 v[108:111], v[146:149], v[218:221], v[108:111]
	v_mfma_f32_16x16x32_bf16 v[100:103], v[154:157], v[218:221], v[100:103]
	v_mfma_f32_16x16x32_bf16 v[92:95], v[146:149], v[226:229], v[92:95]
	v_mfma_f32_16x16x32_bf16 v[84:87], v[154:157], v[226:229], v[84:87]
	v_mfma_f32_16x16x32_bf16 v[76:79], v[146:149], v[234:237], v[76:79]
	v_mfma_f32_16x16x32_bf16 v[68:71], v[154:157], v[234:237], v[68:71]
	s_setprio 0
	s_setprio 1
	v_mfma_f32_16x16x32_bf16 v[120:123], v[158:161], v[192:195], v[120:123]
	v_mfma_f32_16x16x32_bf16 v[112:115], v[184:187], v[192:195], v[112:115]
	v_mfma_f32_16x16x32_bf16 v[104:107], v[158:161], v[214:217], v[104:107]
	v_mfma_f32_16x16x32_bf16 v[96:99], v[184:187], v[214:217], v[96:99]
	v_mfma_f32_16x16x32_bf16 v[88:91], v[158:161], v[222:225], v[88:91]
	v_mfma_f32_16x16x32_bf16 v[80:83], v[184:187], v[222:225], v[80:83]
	v_mfma_f32_16x16x32_bf16 v[72:75], v[158:161], v[230:233], v[72:75]
	v_mfma_f32_16x16x32_bf16 v[64:67], v[184:187], v[230:233], v[64:67]
	v_mfma_f32_16x16x32_bf16 v[120:123], v[180:183], v[196:199], v[120:123]
	v_mfma_f32_16x16x32_bf16 v[112:115], v[188:191], v[196:199], v[112:115]
	v_mfma_f32_16x16x32_bf16 v[104:107], v[180:183], v[218:221], v[104:107]
	v_mfma_f32_16x16x32_bf16 v[96:99], v[188:191], v[218:221], v[96:99]
	v_mfma_f32_16x16x32_bf16 v[88:91], v[180:183], v[226:229], v[88:91]
	v_mfma_f32_16x16x32_bf16 v[80:83], v[188:191], v[226:229], v[80:83]
	v_mfma_f32_16x16x32_bf16 v[72:75], v[180:183], v[234:237], v[72:75]
	v_mfma_f32_16x16x32_bf16 v[64:67], v[188:191], v[234:237], v[64:67]
	s_setprio 0
	s_barrier
	s_add_u32 s24, s20, 0x80
	s_addc_u32 s25, s21, 0
	s_add_u32 s26, s52, 0xfffc0080
	s_addc_u32 s27, s53, -1
	s_add_i32 s28, s60, s41
	s_mov_b32 m0, s28
	ds_read_b128 v[192:195], v145 offset:49152
	ds_read_b128 v[196:199], v145 offset:50176
	ds_read_b128 v[214:217], v145 offset:51200
	ds_read_b128 v[218:221], v145 offset:52224
	ds_read_b128 v[222:225], v145 offset:53248
	ds_read_b128 v[226:229], v145 offset:54272
	ds_read_b128 v[230:233], v145 offset:55296
	ds_read_b128 v[234:237], v145 offset:56320
	global_load_lds_dwordx4 v164, s[24:25]
	s_add_i32 m0, s28, 0x2000
	s_add_u32 s20, s20, 0x40080
	s_addc_u32 s21, s21, 0
	s_add_i32 s28, s61, s41
	global_load_lds_dwordx4 v128, s[24:25]
	s_mov_b32 m0, s28
	s_nop 0
	global_load_lds_dwordx4 v164, s[20:21]
	s_add_i32 m0, s28, 0x2000
	s_nop 0
	global_load_lds_dwordx4 v128, s[20:21]
	s_mov_b32 m0, s49
	s_nop 0
	global_load_lds_dwordx4 v132, s[26:27]
	s_mov_b32 m0, s50
	s_nop 0
	global_load_lds_dwordx4 v130, s[26:27]
	s_waitcnt vmcnt(8)
	s_waitcnt lgkmcnt(0)
	s_barrier
	s_setprio 1
	s_waitcnt lgkmcnt(0)
	v_mfma_f32_16x16x32_bf16 v[60:63], v[138:141], v[192:195], v[60:63]
	v_mfma_f32_16x16x32_bf16 v[52:55], v[150:153], v[192:195], v[52:55]
	v_mfma_f32_16x16x32_bf16 v[44:47], v[138:141], v[214:217], v[44:47]
	v_mfma_f32_16x16x32_bf16 v[36:39], v[150:153], v[214:217], v[36:39]
	v_mfma_f32_16x16x32_bf16 v[28:31], v[138:141], v[222:225], v[28:31]
	v_mfma_f32_16x16x32_bf16 v[20:23], v[150:153], v[222:225], v[20:23]
	v_mfma_f32_16x16x32_bf16 v[12:15], v[138:141], v[230:233], v[12:15]
	v_mfma_f32_16x16x32_bf16 v[4:7], v[150:153], v[230:233], v[4:7]
	v_mfma_f32_16x16x32_bf16 v[60:63], v[146:149], v[196:199], v[60:63]
	v_mfma_f32_16x16x32_bf16 v[52:55], v[154:157], v[196:199], v[52:55]
	v_mfma_f32_16x16x32_bf16 v[44:47], v[146:149], v[218:221], v[44:47]
	v_mfma_f32_16x16x32_bf16 v[36:39], v[154:157], v[218:221], v[36:39]
	v_mfma_f32_16x16x32_bf16 v[28:31], v[146:149], v[226:229], v[28:31]
	v_mfma_f32_16x16x32_bf16 v[20:23], v[154:157], v[226:229], v[20:23]
	v_mfma_f32_16x16x32_bf16 v[12:15], v[146:149], v[234:237], v[12:15]
	v_mfma_f32_16x16x32_bf16 v[4:7], v[154:157], v[234:237], v[4:7]
	s_setprio 0
	s_setprio 1
	v_mfma_f32_16x16x32_bf16 v[56:59], v[158:161], v[192:195], v[56:59]
	v_mfma_f32_16x16x32_bf16 v[48:51], v[184:187], v[192:195], v[48:51]
	v_mfma_f32_16x16x32_bf16 v[40:43], v[158:161], v[214:217], v[40:43]
	v_mfma_f32_16x16x32_bf16 v[32:35], v[184:187], v[214:217], v[32:35]
	v_mfma_f32_16x16x32_bf16 v[24:27], v[158:161], v[222:225], v[24:27]
	v_mfma_f32_16x16x32_bf16 v[16:19], v[184:187], v[222:225], v[16:19]
	v_mfma_f32_16x16x32_bf16 v[8:11], v[158:161], v[230:233], v[8:11]
	v_mfma_f32_16x16x32_bf16 v[0:3], v[184:187], v[230:233], v[0:3]
	v_mfma_f32_16x16x32_bf16 v[56:59], v[180:183], v[196:199], v[56:59]
	v_mfma_f32_16x16x32_bf16 v[48:51], v[188:191], v[196:199], v[48:51]
	v_mfma_f32_16x16x32_bf16 v[40:43], v[180:183], v[218:221], v[40:43]
	v_mfma_f32_16x16x32_bf16 v[32:35], v[188:191], v[218:221], v[32:35]
	v_mfma_f32_16x16x32_bf16 v[24:27], v[180:183], v[226:229], v[24:27]
	v_mfma_f32_16x16x32_bf16 v[16:19], v[188:191], v[226:229], v[16:19]
	v_mfma_f32_16x16x32_bf16 v[8:11], v[180:183], v[234:237], v[8:11]
	v_mfma_f32_16x16x32_bf16 v[0:3], v[188:191], v[234:237], v[0:3]
	s_setprio 0
	s_barrier
	s_add_i32 s59, s59, 2
	s_add_u32 s57, s57, 0x100
	s_addc_u32 s58, s58, 0
	s_add_u32 s18, s18, 0x100
	s_addc_u32 s19, s19, 0
	s_cmp_gt_u32 s59, 13
	s_cbranch_scc0 .LBB0_1492
	s_and_b64 vcc, exec, s[6:7]
	s_cbranch_vccz .LBB0_1495
	s_barrier
